# GU GEMM K-loop as merged 64-MFMA phases (4 barriers per 2 K-tiles), role-split staging, paired M0 DMA with offset:-4096, 2 of the trailing half's DMA issued inside its MFMA segment with counted waits;
# baseline (speedup 1.0000x reference)
.LBB0_1083:
	v_lshrrev_b32_e32 v18, 1, v8
	v_and_b32_e32 v18, 24, v18
	v_readlane_b32 s52, v255, 45
	v_and_b32_e32 v9, 15, v8
	v_lshlrev_b32_e32 v19, 1, v18
	v_lshlrev_b32_e32 v8, 2, v8
	s_lshl_b32 s21, s21, 5
	v_readlane_b32 s53, v255, 46
	v_lshl_or_b32 v144, s33, 6, v9
	v_lshl_or_b32 v9, v9, 6, v19
	s_lshl_b32 s30, s33, 13
	v_and_b32_e32 v8, 32, v8
	s_and_b32 s21, s21, 0x60
	v_lshl_add_u64 v[10:11], s[52:53], 0, v[0:1]
	v_mov_b32_e32 v131, v1
	v_readlane_b32 s40, v254, 47
	v_bitop3_b32 v19, v9, s30, v8 bitop3:0xde
	s_lshl_b32 s30, s21, 7
	v_lshl_add_u64 v[12:13], s[52:53], 0, v[130:131]
	v_mov_b32_e32 v135, v1
	v_readlane_b32 s41, v254, 48
	v_bitop3_b32 v145, v9, s30, v8 bitop3:0xde
	s_add_i32 m0, s55, 0x18000
	v_lshl_add_u64 v[8:9], v[10:11], 0, s[38:39]
	v_lshl_add_u64 v[14:15], s[40:41], 0, v[134:135]
	v_mov_b32_e32 v133, v1
	s_waitcnt vmcnt(0)
	s_barrier
	global_load_lds_dwordx4 v[8:9], off
	v_lshl_add_u64 v[8:9], v[12:13], 0, s[38:39]
	s_add_i32 m0, s55, 0x1a000
	s_add_i32 s36, s55, 0x8000
	v_lshl_add_u64 v[16:17], s[40:41], 0, v[132:133]
	global_load_lds_dwordx4 v[8:9], off
	v_lshl_add_u64 v[8:9], v[14:15], 0, s[38:39]
	s_mov_b32 m0, s36
	s_add_i32 s37, s55, 0xa000
	v_readlane_b32 s30, v255, 47
	global_load_lds_dwordx4 v[8:9], off
	v_lshl_add_u64 v[8:9], v[16:17], 0, s[38:39]
	s_mov_b32 m0, s37
	v_readlane_b32 s31, v255, 48
	global_load_lds_dwordx4 v[8:9], off
	s_add_i32 m0, s55, 0x1c000
	v_lshl_add_u64 v[8:9], s[30:31], 0, v[0:1]
	global_load_lds_dwordx4 v[8:9], off
	v_lshl_add_u64 v[8:9], s[30:31], 0, v[130:131]
	s_add_i32 m0, s55, 0x1e000
	s_cmpk_lt_u32 s20, 0x100
	global_load_lds_dwordx4 v[8:9], off
	v_lshlrev_b32_e32 v8, 15, v6
	v_and_b32_e32 v8, 0xffff0000, v8
	v_lshl_add_u32 v5, v5, 12, v8
	v_and_b32_e32 v6, 1, v6
	v_lshl_or_b32 v5, v6, 6, v5
	v_lshl_add_u32 v136, v7, 1, v5
	v_lshlrev_b32_e32 v5, 15, v2
	v_and_b32_e32 v5, 0xffff0000, v5
	s_waitcnt vmcnt(6)
	v_or_b32_e32 v146, s21, v18
	v_lshl_add_u32 v3, v3, 12, v5
	v_and_b32_e32 v2, 1, v2
	v_readlane_b32 s20, v254, 45
	v_lshl_or_b32 v2, v2, 6, v3
	v_readlane_b32 s21, v254, 46
	s_cselect_b64 s[64:65], -1, 0
	v_mov_b32_e32 v137, v1
	v_lshl_add_u32 v138, v4, 1, v2
	v_mov_b32_e32 v139, v1
	s_mov_b32 s70, 0
	v_add_u32_e32 v147, 0, v19
	v_readlane_b32 s33, v254, 42
	s_mov_b32 s48, s20
	s_mov_b64 s[20:21], s[40:41]
	s_add_u32 s98, s20, 0x80080
	s_addc_u32 s99, s21, 0
	s_add_i32 m0, s55, 0xc000
	s_nop 0
	global_load_lds_dwordx4 v134, s[98:99]
	s_add_i32 m0, s55, 0xe000
	s_nop 0
	global_load_lds_dwordx4 v132, s[98:99]
	s_waitcnt vmcnt(0)
	s_barrier
	s_branch .LBB0_1086

;     __device__ __forceinline__ void init(f32x4 (&acc)[2][2][4][2], const Unit&, int, int, int, int) const {
; #pragma unroll
;         for (int a = 0; a < 2; ++a)
; #pragma unroll
;             for (int b = 0; b < 2; ++b)
; #pragma unroll
;                 for (int m = 0; m < 4; ++m)
; #pragma unroll
;                     for (int n = 0; n < 2; ++n) acc[a][b][m][n] = (f32x4){0.f, 0.f, 0.f, 0.f};
;     }
.LBB0_1088:
	s_ashr_i32 s43, s42, 31
	s_lshl_b64 s[44:45], s[42:43], 20
	s_add_u32 s44, s68, s44
	s_addc_u32 s45, s69, s45
	s_and_b64 s[50:51], s[40:41], exec
	s_cselect_b32 s43, s45, s21
	s_cselect_b32 s49, s44, s20
	s_ashr_i32 s67, s66, 31
	s_lshl_b64 s[50:51], s[66:67], 20
	s_add_u32 s50, s46, s50
	s_addc_u32 s51, s47, s51
	s_and_b64 s[74:75], s[40:41], exec
	s_cselect_b32 s67, s51, s53
	s_cselect_b32 s71, s50, s52
	s_add_u32 s20, s20, 0x80080
	s_addc_u32 s21, s21, 0
	s_add_u32 s74, s52, 0x100
	v_mov_b32_e32 v2, 0
	s_addc_u32 s75, s53, 0
	s_mov_b32 s76, -2
	v_mov_b32_e32 v3, v2
	v_mov_b32_e32 v4, v2
	v_mov_b32_e32 v5, v2
	v_mov_b32_e32 v10, v2
	v_mov_b32_e32 v11, v2
	v_mov_b32_e32 v12, v2
	v_mov_b32_e32 v13, v2
	v_mov_b32_e32 v18, v2
	v_mov_b32_e32 v19, v2
	v_mov_b32_e32 v20, v2
	v_mov_b32_e32 v21, v2
	v_mov_b32_e32 v26, v2
	v_mov_b32_e32 v27, v2
	v_mov_b32_e32 v28, v2
	v_mov_b32_e32 v29, v2
	v_mov_b32_e32 v34, v2
	v_mov_b32_e32 v35, v2
	v_mov_b32_e32 v36, v2
	v_mov_b32_e32 v37, v2
	v_mov_b32_e32 v42, v2
	v_mov_b32_e32 v43, v2
	v_mov_b32_e32 v44, v2
	v_mov_b32_e32 v45, v2
	v_mov_b32_e32 v50, v2
	v_mov_b32_e32 v51, v2
	v_mov_b32_e32 v52, v2
	v_mov_b32_e32 v53, v2
	v_mov_b32_e32 v58, v2
	v_mov_b32_e32 v59, v2
	v_mov_b32_e32 v60, v2
	v_mov_b32_e32 v61, v2
	v_mov_b32_e32 v6, v2
	v_mov_b32_e32 v7, v2
	v_mov_b32_e32 v8, v2
	v_mov_b32_e32 v9, v2
	v_mov_b32_e32 v14, v2
	v_mov_b32_e32 v15, v2
	v_mov_b32_e32 v16, v2
	v_mov_b32_e32 v17, v2
	v_mov_b32_e32 v22, v2
	v_mov_b32_e32 v23, v2
	v_mov_b32_e32 v24, v2
	v_mov_b32_e32 v25, v2
	v_mov_b32_e32 v30, v2
	v_mov_b32_e32 v31, v2
	v_mov_b32_e32 v32, v2
	v_mov_b32_e32 v33, v2
	v_mov_b32_e32 v38, v2
	v_mov_b32_e32 v39, v2
	v_mov_b32_e32 v40, v2
	v_mov_b32_e32 v41, v2
	v_mov_b32_e32 v46, v2
	v_mov_b32_e32 v47, v2
	v_mov_b32_e32 v48, v2
	v_mov_b32_e32 v49, v2
	v_mov_b32_e32 v54, v2
	v_mov_b32_e32 v55, v2
	v_mov_b32_e32 v56, v2
	v_mov_b32_e32 v57, v2
	v_mov_b32_e32 v62, v2
	v_mov_b32_e32 v63, v2
	v_mov_b32_e32 v64, v2
	v_mov_b32_e32 v65, v2
	v_mov_b32_e32 v66, v2
	v_mov_b32_e32 v67, v2
	v_mov_b32_e32 v68, v2
	v_mov_b32_e32 v69, v2
	v_mov_b32_e32 v74, v2
	v_mov_b32_e32 v75, v2
	v_mov_b32_e32 v76, v2
	v_mov_b32_e32 v77, v2
	v_mov_b32_e32 v82, v2
	v_mov_b32_e32 v83, v2
	v_mov_b32_e32 v84, v2
	v_mov_b32_e32 v85, v2
	v_mov_b32_e32 v90, v2
	v_mov_b32_e32 v91, v2
	v_mov_b32_e32 v92, v2
	v_mov_b32_e32 v93, v2
	v_mov_b32_e32 v98, v2
	v_mov_b32_e32 v99, v2
	v_mov_b32_e32 v100, v2
	v_mov_b32_e32 v101, v2
	v_mov_b32_e32 v106, v2
	v_mov_b32_e32 v107, v2
	v_mov_b32_e32 v108, v2
	v_mov_b32_e32 v109, v2
	v_mov_b32_e32 v114, v2
	v_mov_b32_e32 v115, v2
	v_mov_b32_e32 v116, v2
	v_mov_b32_e32 v117, v2
	v_mov_b32_e32 v122, v2
	v_mov_b32_e32 v123, v2
	v_mov_b32_e32 v124, v2
	v_mov_b32_e32 v125, v2
	v_mov_b32_e32 v70, v2
	v_mov_b32_e32 v71, v2
	v_mov_b32_e32 v72, v2
	v_mov_b32_e32 v73, v2
	v_mov_b32_e32 v78, v2
	v_mov_b32_e32 v79, v2
	v_mov_b32_e32 v80, v2
	v_mov_b32_e32 v81, v2
	v_mov_b32_e32 v86, v2
	v_mov_b32_e32 v87, v2
	v_mov_b32_e32 v88, v2
	v_mov_b32_e32 v89, v2
	v_mov_b32_e32 v94, v2
	v_mov_b32_e32 v95, v2
	v_mov_b32_e32 v96, v2
	v_mov_b32_e32 v97, v2
	v_mov_b32_e32 v102, v2
	v_mov_b32_e32 v103, v2
	v_mov_b32_e32 v104, v2
	v_mov_b32_e32 v105, v2
	v_mov_b32_e32 v110, v2
	v_mov_b32_e32 v111, v2
	v_mov_b32_e32 v112, v2
	v_mov_b32_e32 v113, v2
	v_mov_b32_e32 v118, v2
	v_mov_b32_e32 v119, v2
	v_mov_b32_e32 v120, v2
	v_mov_b32_e32 v121, v2
	v_mov_b32_e32 v126, v2
	v_mov_b32_e32 v127, v2
	v_mov_b32_e32 v128, v2
	v_mov_b32_e32 v129, v2
	v_add_u32_e32 v172, 0x10000, v145
	v_add_u32_e32 v173, 0x14000, v145
	v_add_u32_e32 v174, 0x18000, v145
	v_add_u32_e32 v250, 0x1c000, v145
	s_and_b64 vcc, exec, s[64:65]
	s_cbranch_vccz .Lgd_prey
	v_add_u32_e32 v130, 0x1000, v0
	v_add_u32_e32 v131, 0x20000, v0
	v_add_u32_e32 v133, 0x41000, v0
	v_add_u32_e32 v135, 0x60000, v0
	v_add_u32_e32 v188, 0x81000, v0
	v_add_u32_e32 v190, 0xa0000, v0
	v_add_u32_e32 v192, 0xc1000, v0
	v_add_u32_e32 v194, 0xe0000, v0
	s_branch .Lgd_prej
.Lgd_prey:
	v_add_u32_e32 v130, 0x21000, v134
	v_add_u32_e32 v131, 0x0, v132
	v_add_u32_e32 v133, 0xa1000, v134
	v_add_u32_e32 v135, 0x80000, v132
	v_add_u32_e32 v188, 0x0, v134
	v_add_u32_e32 v190, 0xfffe1000, v134
	v_add_u32_e32 v192, 0x80000, v134
	v_add_u32_e32 v194, 0x61000, v134
.Lgd_prej:
.LBB0_1089:
	s_add_u32 s30, s20, 0xfff80080
	s_addc_u32 s31, s21, -1
	s_cmp_eq_u32 s76, 28
	s_cselect_b32 s99, s43, s31
	s_cselect_b32 s98, s49, s30
	s_cselect_b32 s53, s67, s75
	s_cselect_b32 s52, s71, s74
	s_add_u32 s30, s20, 0xfff80000
	s_addc_u32 s31, s21, -1
	s_add_u32 s100, s74, 0xffffff80
	s_addc_u32 s101, s75, -1
	s_and_b64 vcc, exec, s[64:65]
	s_cbranch_vccz .Lgd_y1
	s_add_i32 m0, s55, 0x19000
	ds_read_b128 v[198:201], v147
	ds_read_b128 v[206:209], v147 offset:2048
	global_load_lds_dwordx4 v130, s[100:101] offset:-4096
	ds_read_b128 v[214:217], v147 offset:4096
	ds_read_b128 v[222:225], v147 offset:6144
	global_load_lds_dwordx4 v131, s[100:101]
	ds_read_b128 v[202:205], v147 offset:1024
	ds_read_b128 v[210:213], v147 offset:3072
	s_add_i32 m0, s55, 0x1b000
	ds_read_b128 v[218:221], v147 offset:5120
	ds_read_b128 v[226:229], v147 offset:7168
	global_load_lds_dwordx4 v133, s[100:101] offset:-4096
	ds_read_b128 v[140:143], v172
	ds_read_b128 v[152:155], v172 offset:2048
	global_load_lds_dwordx4 v135, s[100:101]
	ds_read_b128 v[148:151], v172 offset:1024
	ds_read_b128 v[156:159], v172 offset:3072
	s_add_i32 m0, s55, 0x1d000
	ds_read_b128 v[160:163], v173
	ds_read_b128 v[176:179], v173 offset:2048
	global_load_lds_dwordx4 v188, s[100:101] offset:-4096
	ds_read_b128 v[168:171], v173 offset:1024
	ds_read_b128 v[180:183], v173 offset:3072
	global_load_lds_dwordx4 v190, s[100:101]
	ds_read_b128 v[234:237], v147 offset:16384
	ds_read_b128 v[242:245], v147 offset:18432
	s_add_i32 m0, s55, 0x1f000
	ds_read_b128 v[136:139], v147 offset:20480
	ds_read_b128 v[184:187], v147 offset:22528
	global_load_lds_dwordx4 v192, s[100:101] offset:-4096
	ds_read_b128 v[238:241], v147 offset:17408
	ds_read_b128 v[246:249], v147 offset:19456
	global_load_lds_dwordx4 v194, s[100:101]
	ds_read_b128 v[230:233], v147 offset:21504
	ds_read_b128 v[164:167], v147 offset:23552
	s_setprio 1
	s_waitcnt lgkmcnt(0)
	s_barrier
	v_mfma_f32_16x16x32_bf16 v[126:129], v[140:143], v[198:201], v[126:129]
	v_mfma_f32_16x16x32_bf16 v[118:121], v[152:155], v[198:201], v[118:121]
	v_mfma_f32_16x16x32_bf16 v[110:113], v[140:143], v[206:209], v[110:113]
	v_mfma_f32_16x16x32_bf16 v[102:105], v[152:155], v[206:209], v[102:105]
	v_mfma_f32_16x16x32_bf16 v[94:97], v[140:143], v[214:217], v[94:97]
	v_mfma_f32_16x16x32_bf16 v[86:89], v[152:155], v[214:217], v[86:89]
	v_mfma_f32_16x16x32_bf16 v[78:81], v[140:143], v[222:225], v[78:81]
	v_mfma_f32_16x16x32_bf16 v[70:73], v[152:155], v[222:225], v[70:73]
	v_mfma_f32_16x16x32_bf16 v[126:129], v[148:151], v[202:205], v[126:129]
	v_mfma_f32_16x16x32_bf16 v[118:121], v[156:159], v[202:205], v[118:121]
	v_mfma_f32_16x16x32_bf16 v[110:113], v[148:151], v[210:213], v[110:113]
	v_mfma_f32_16x16x32_bf16 v[102:105], v[156:159], v[210:213], v[102:105]
	v_mfma_f32_16x16x32_bf16 v[94:97], v[148:151], v[218:221], v[94:97]
	v_mfma_f32_16x16x32_bf16 v[86:89], v[156:159], v[218:221], v[86:89]
	v_mfma_f32_16x16x32_bf16 v[78:81], v[148:151], v[226:229], v[78:81]
	v_mfma_f32_16x16x32_bf16 v[70:73], v[156:159], v[226:229], v[70:73]
	v_mfma_f32_16x16x32_bf16 v[122:125], v[160:163], v[198:201], v[122:125]
	v_mfma_f32_16x16x32_bf16 v[114:117], v[176:179], v[198:201], v[114:117]
	v_mfma_f32_16x16x32_bf16 v[106:109], v[160:163], v[206:209], v[106:109]
	v_mfma_f32_16x16x32_bf16 v[98:101], v[176:179], v[206:209], v[98:101]
	v_mfma_f32_16x16x32_bf16 v[90:93], v[160:163], v[214:217], v[90:93]
	v_mfma_f32_16x16x32_bf16 v[82:85], v[176:179], v[214:217], v[82:85]
	v_mfma_f32_16x16x32_bf16 v[74:77], v[160:163], v[222:225], v[74:77]
	v_mfma_f32_16x16x32_bf16 v[66:69], v[176:179], v[222:225], v[66:69]
	v_mfma_f32_16x16x32_bf16 v[122:125], v[168:171], v[202:205], v[122:125]
	v_mfma_f32_16x16x32_bf16 v[114:117], v[180:183], v[202:205], v[114:117]
	v_mfma_f32_16x16x32_bf16 v[106:109], v[168:171], v[210:213], v[106:109]
	v_mfma_f32_16x16x32_bf16 v[98:101], v[180:183], v[210:213], v[98:101]
	v_mfma_f32_16x16x32_bf16 v[90:93], v[168:171], v[218:221], v[90:93]
	v_mfma_f32_16x16x32_bf16 v[82:85], v[180:183], v[218:221], v[82:85]
	v_mfma_f32_16x16x32_bf16 v[74:77], v[168:171], v[226:229], v[74:77]
	v_mfma_f32_16x16x32_bf16 v[66:69], v[180:183], v[226:229], v[66:69]
	v_mfma_f32_16x16x32_bf16 v[62:65], v[140:143], v[234:237], v[62:65]
	v_mfma_f32_16x16x32_bf16 v[54:57], v[152:155], v[234:237], v[54:57]
	v_mfma_f32_16x16x32_bf16 v[46:49], v[140:143], v[242:245], v[46:49]
	v_mfma_f32_16x16x32_bf16 v[38:41], v[152:155], v[242:245], v[38:41]
	v_mfma_f32_16x16x32_bf16 v[30:33], v[140:143], v[136:139], v[30:33]
	v_mfma_f32_16x16x32_bf16 v[22:25], v[152:155], v[136:139], v[22:25]
	v_mfma_f32_16x16x32_bf16 v[14:17], v[140:143], v[184:187], v[14:17]
	v_mfma_f32_16x16x32_bf16 v[6:9], v[152:155], v[184:187], v[6:9]
	v_mfma_f32_16x16x32_bf16 v[62:65], v[148:151], v[238:241], v[62:65]
	v_mfma_f32_16x16x32_bf16 v[54:57], v[156:159], v[238:241], v[54:57]
	v_mfma_f32_16x16x32_bf16 v[46:49], v[148:151], v[246:249], v[46:49]
	v_mfma_f32_16x16x32_bf16 v[38:41], v[156:159], v[246:249], v[38:41]
	v_mfma_f32_16x16x32_bf16 v[30:33], v[148:151], v[230:233], v[30:33]
	v_mfma_f32_16x16x32_bf16 v[22:25], v[156:159], v[230:233], v[22:25]
	v_mfma_f32_16x16x32_bf16 v[14:17], v[148:151], v[164:167], v[14:17]
	v_mfma_f32_16x16x32_bf16 v[6:9], v[156:159], v[164:167], v[6:9]
	v_mfma_f32_16x16x32_bf16 v[58:61], v[160:163], v[234:237], v[58:61]
	v_mfma_f32_16x16x32_bf16 v[50:53], v[176:179], v[234:237], v[50:53]
	v_mfma_f32_16x16x32_bf16 v[42:45], v[160:163], v[242:245], v[42:45]
	v_mfma_f32_16x16x32_bf16 v[34:37], v[176:179], v[242:245], v[34:37]
	v_mfma_f32_16x16x32_bf16 v[26:29], v[160:163], v[136:139], v[26:29]
	v_mfma_f32_16x16x32_bf16 v[18:21], v[176:179], v[136:139], v[18:21]
	v_mfma_f32_16x16x32_bf16 v[10:13], v[160:163], v[184:187], v[10:13]
	v_mfma_f32_16x16x32_bf16 v[2:5], v[176:179], v[184:187], v[2:5]
	v_mfma_f32_16x16x32_bf16 v[58:61], v[168:171], v[238:241], v[58:61]
	v_mfma_f32_16x16x32_bf16 v[50:53], v[180:183], v[238:241], v[50:53]
	v_mfma_f32_16x16x32_bf16 v[42:45], v[168:171], v[246:249], v[42:45]
	v_mfma_f32_16x16x32_bf16 v[34:37], v[180:183], v[246:249], v[34:37]
	v_mfma_f32_16x16x32_bf16 v[26:29], v[168:171], v[230:233], v[26:29]
	v_mfma_f32_16x16x32_bf16 v[18:21], v[180:183], v[230:233], v[18:21]
	v_mfma_f32_16x16x32_bf16 v[10:13], v[168:171], v[164:167], v[10:13]
	v_mfma_f32_16x16x32_bf16 v[2:5], v[180:183], v[164:167], v[2:5]
	s_waitcnt vmcnt(0)
	s_barrier
	s_setprio 0
	s_branch .Lgd_j1
.Lgd_y1:
	s_add_i32 m0, s55, 0xa000
	ds_read_b128 v[198:201], v147
	ds_read_b128 v[206:209], v147 offset:2048
	global_load_lds_dwordx4 v130, s[30:31] offset:-4096
	ds_read_b128 v[214:217], v147 offset:4096
	ds_read_b128 v[222:225], v147 offset:6144
	ds_read_b128 v[202:205], v147 offset:1024
	global_load_lds_dwordx4 v131, s[30:31]
	ds_read_b128 v[210:213], v147 offset:3072
	ds_read_b128 v[218:221], v147 offset:5120
	ds_read_b128 v[226:229], v147 offset:7168
	s_add_i32 m0, s55, 0xe000
	ds_read_b128 v[140:143], v172
	ds_read_b128 v[152:155], v172 offset:2048
	global_load_lds_dwordx4 v133, s[30:31] offset:-4096
	ds_read_b128 v[148:151], v172 offset:1024
	ds_read_b128 v[156:159], v172 offset:3072
	ds_read_b128 v[160:163], v173
	global_load_lds_dwordx4 v135, s[30:31]
	ds_read_b128 v[176:179], v173 offset:2048
	ds_read_b128 v[168:171], v173 offset:1024
	ds_read_b128 v[180:183], v173 offset:3072
	s_add_i32 m0, s55, 0x0
	ds_read_b128 v[234:237], v147 offset:16384
	ds_read_b128 v[242:245], v147 offset:18432
	global_load_lds_dwordx4 v190, s[98:99] offset:-4096
	ds_read_b128 v[136:139], v147 offset:20480
	ds_read_b128 v[184:187], v147 offset:22528
	ds_read_b128 v[238:241], v147 offset:17408
	global_load_lds_dwordx4 v188, s[98:99]
	ds_read_b128 v[246:249], v147 offset:19456
	ds_read_b128 v[230:233], v147 offset:21504
	ds_read_b128 v[164:167], v147 offset:23552
	s_setprio 1
	s_waitcnt vmcnt(6) lgkmcnt(0)
	s_barrier
	v_mfma_f32_16x16x32_bf16 v[126:129], v[140:143], v[198:201], v[126:129]
	v_mfma_f32_16x16x32_bf16 v[118:121], v[152:155], v[198:201], v[118:121]
	s_add_i32 m0, s55, 0x4000
	v_mfma_f32_16x16x32_bf16 v[110:113], v[140:143], v[206:209], v[110:113]
	v_mfma_f32_16x16x32_bf16 v[102:105], v[152:155], v[206:209], v[102:105]
	global_load_lds_dwordx4 v194, s[98:99] offset:-4096
	v_mfma_f32_16x16x32_bf16 v[94:97], v[140:143], v[214:217], v[94:97]
	v_mfma_f32_16x16x32_bf16 v[86:89], v[152:155], v[214:217], v[86:89]
	v_mfma_f32_16x16x32_bf16 v[78:81], v[140:143], v[222:225], v[78:81]
	v_mfma_f32_16x16x32_bf16 v[70:73], v[152:155], v[222:225], v[70:73]
	v_mfma_f32_16x16x32_bf16 v[126:129], v[148:151], v[202:205], v[126:129]
	v_mfma_f32_16x16x32_bf16 v[118:121], v[156:159], v[202:205], v[118:121]
	v_mfma_f32_16x16x32_bf16 v[110:113], v[148:151], v[210:213], v[110:113]
	v_mfma_f32_16x16x32_bf16 v[102:105], v[156:159], v[210:213], v[102:105]
	global_load_lds_dwordx4 v192, s[98:99]
	v_mfma_f32_16x16x32_bf16 v[94:97], v[148:151], v[218:221], v[94:97]
	v_mfma_f32_16x16x32_bf16 v[86:89], v[156:159], v[218:221], v[86:89]
	v_mfma_f32_16x16x32_bf16 v[78:81], v[148:151], v[226:229], v[78:81]
	v_mfma_f32_16x16x32_bf16 v[70:73], v[156:159], v[226:229], v[70:73]
	v_mfma_f32_16x16x32_bf16 v[122:125], v[160:163], v[198:201], v[122:125]
	v_mfma_f32_16x16x32_bf16 v[114:117], v[176:179], v[198:201], v[114:117]
	v_mfma_f32_16x16x32_bf16 v[106:109], v[160:163], v[206:209], v[106:109]
	v_mfma_f32_16x16x32_bf16 v[98:101], v[176:179], v[206:209], v[98:101]
	v_mfma_f32_16x16x32_bf16 v[90:93], v[160:163], v[214:217], v[90:93]
	v_mfma_f32_16x16x32_bf16 v[82:85], v[176:179], v[214:217], v[82:85]
	v_mfma_f32_16x16x32_bf16 v[74:77], v[160:163], v[222:225], v[74:77]
	v_mfma_f32_16x16x32_bf16 v[66:69], v[176:179], v[222:225], v[66:69]
	v_mfma_f32_16x16x32_bf16 v[122:125], v[168:171], v[202:205], v[122:125]
	v_mfma_f32_16x16x32_bf16 v[114:117], v[180:183], v[202:205], v[114:117]
	v_mfma_f32_16x16x32_bf16 v[106:109], v[168:171], v[210:213], v[106:109]
	v_mfma_f32_16x16x32_bf16 v[98:101], v[180:183], v[210:213], v[98:101]
	v_mfma_f32_16x16x32_bf16 v[90:93], v[168:171], v[218:221], v[90:93]
	v_mfma_f32_16x16x32_bf16 v[82:85], v[180:183], v[218:221], v[82:85]
	v_mfma_f32_16x16x32_bf16 v[74:77], v[168:171], v[226:229], v[74:77]
	v_mfma_f32_16x16x32_bf16 v[66:69], v[180:183], v[226:229], v[66:69]
	v_mfma_f32_16x16x32_bf16 v[62:65], v[140:143], v[234:237], v[62:65]
	v_mfma_f32_16x16x32_bf16 v[54:57], v[152:155], v[234:237], v[54:57]
	v_mfma_f32_16x16x32_bf16 v[46:49], v[140:143], v[242:245], v[46:49]
	v_mfma_f32_16x16x32_bf16 v[38:41], v[152:155], v[242:245], v[38:41]
	v_mfma_f32_16x16x32_bf16 v[30:33], v[140:143], v[136:139], v[30:33]
	v_mfma_f32_16x16x32_bf16 v[22:25], v[152:155], v[136:139], v[22:25]
	v_mfma_f32_16x16x32_bf16 v[14:17], v[140:143], v[184:187], v[14:17]
	v_mfma_f32_16x16x32_bf16 v[6:9], v[152:155], v[184:187], v[6:9]
	v_mfma_f32_16x16x32_bf16 v[62:65], v[148:151], v[238:241], v[62:65]
	v_mfma_f32_16x16x32_bf16 v[54:57], v[156:159], v[238:241], v[54:57]
	v_mfma_f32_16x16x32_bf16 v[46:49], v[148:151], v[246:249], v[46:49]
	v_mfma_f32_16x16x32_bf16 v[38:41], v[156:159], v[246:249], v[38:41]
	v_mfma_f32_16x16x32_bf16 v[30:33], v[148:151], v[230:233], v[30:33]
	v_mfma_f32_16x16x32_bf16 v[22:25], v[156:159], v[230:233], v[22:25]
	v_mfma_f32_16x16x32_bf16 v[14:17], v[148:151], v[164:167], v[14:17]
	v_mfma_f32_16x16x32_bf16 v[6:9], v[156:159], v[164:167], v[6:9]
	v_mfma_f32_16x16x32_bf16 v[58:61], v[160:163], v[234:237], v[58:61]
	v_mfma_f32_16x16x32_bf16 v[50:53], v[176:179], v[234:237], v[50:53]
	v_mfma_f32_16x16x32_bf16 v[42:45], v[160:163], v[242:245], v[42:45]
	v_mfma_f32_16x16x32_bf16 v[34:37], v[176:179], v[242:245], v[34:37]
	v_mfma_f32_16x16x32_bf16 v[26:29], v[160:163], v[136:139], v[26:29]
	v_mfma_f32_16x16x32_bf16 v[18:21], v[176:179], v[136:139], v[18:21]
	v_mfma_f32_16x16x32_bf16 v[10:13], v[160:163], v[184:187], v[10:13]
	v_mfma_f32_16x16x32_bf16 v[2:5], v[176:179], v[184:187], v[2:5]
	v_mfma_f32_16x16x32_bf16 v[58:61], v[168:171], v[238:241], v[58:61]
	v_mfma_f32_16x16x32_bf16 v[50:53], v[180:183], v[238:241], v[50:53]
	v_mfma_f32_16x16x32_bf16 v[42:45], v[168:171], v[246:249], v[42:45]
	v_mfma_f32_16x16x32_bf16 v[34:37], v[180:183], v[246:249], v[34:37]
	v_mfma_f32_16x16x32_bf16 v[26:29], v[168:171], v[230:233], v[26:29]
	v_mfma_f32_16x16x32_bf16 v[18:21], v[180:183], v[230:233], v[18:21]
	v_mfma_f32_16x16x32_bf16 v[10:13], v[168:171], v[164:167], v[10:13]
	v_mfma_f32_16x16x32_bf16 v[2:5], v[180:183], v[164:167], v[2:5]
	s_waitcnt vmcnt(2)
	s_barrier
	s_setprio 0
.Lgd_j1:
	s_add_u32 s30, s98, 0x80
	s_addc_u32 s31, s99, 0
	s_and_b64 vcc, exec, s[64:65]
	s_cbranch_vccz .Lgd_y2
	s_add_i32 m0, s55, 0x11000
	ds_read_b128 v[198:201], v147 offset:32768
	ds_read_b128 v[206:209], v147 offset:34816
	global_load_lds_dwordx4 v130, s[52:53] offset:-4096
	ds_read_b128 v[214:217], v147 offset:36864
	ds_read_b128 v[222:225], v147 offset:38912
	global_load_lds_dwordx4 v131, s[52:53]
	ds_read_b128 v[202:205], v147 offset:33792
	ds_read_b128 v[210:213], v147 offset:35840
	s_add_i32 m0, s55, 0x13000
	ds_read_b128 v[218:221], v147 offset:37888
	ds_read_b128 v[226:229], v147 offset:39936
	global_load_lds_dwordx4 v133, s[52:53] offset:-4096
	ds_read_b128 v[140:143], v174
	ds_read_b128 v[152:155], v174 offset:2048
	global_load_lds_dwordx4 v135, s[52:53]
	ds_read_b128 v[148:151], v174 offset:1024
	ds_read_b128 v[156:159], v174 offset:3072
	s_add_i32 m0, s55, 0x15000
	ds_read_b128 v[160:163], v250
	ds_read_b128 v[176:179], v250 offset:2048
	global_load_lds_dwordx4 v188, s[52:53] offset:-4096
	ds_read_b128 v[168:171], v250 offset:1024
	ds_read_b128 v[180:183], v250 offset:3072
	global_load_lds_dwordx4 v190, s[52:53]
	ds_read_b128 v[234:237], v147 offset:49152
	ds_read_b128 v[242:245], v147 offset:51200
	s_add_i32 m0, s55, 0x17000
	ds_read_b128 v[136:139], v147 offset:53248
	ds_read_b128 v[184:187], v147 offset:55296
	global_load_lds_dwordx4 v192, s[52:53] offset:-4096
	ds_read_b128 v[238:241], v147 offset:50176
	ds_read_b128 v[246:249], v147 offset:52224
	global_load_lds_dwordx4 v194, s[52:53]
	ds_read_b128 v[230:233], v147 offset:54272
	ds_read_b128 v[164:167], v147 offset:56320
	s_setprio 1
	s_waitcnt lgkmcnt(0)
	s_barrier
	v_mfma_f32_16x16x32_bf16 v[126:129], v[140:143], v[198:201], v[126:129]
	v_mfma_f32_16x16x32_bf16 v[118:121], v[152:155], v[198:201], v[118:121]
	v_mfma_f32_16x16x32_bf16 v[110:113], v[140:143], v[206:209], v[110:113]
	v_mfma_f32_16x16x32_bf16 v[102:105], v[152:155], v[206:209], v[102:105]
	v_mfma_f32_16x16x32_bf16 v[94:97], v[140:143], v[214:217], v[94:97]
	v_mfma_f32_16x16x32_bf16 v[86:89], v[152:155], v[214:217], v[86:89]
	v_mfma_f32_16x16x32_bf16 v[78:81], v[140:143], v[222:225], v[78:81]
	v_mfma_f32_16x16x32_bf16 v[70:73], v[152:155], v[222:225], v[70:73]
	v_mfma_f32_16x16x32_bf16 v[126:129], v[148:151], v[202:205], v[126:129]
	v_mfma_f32_16x16x32_bf16 v[118:121], v[156:159], v[202:205], v[118:121]
	v_mfma_f32_16x16x32_bf16 v[110:113], v[148:151], v[210:213], v[110:113]
	v_mfma_f32_16x16x32_bf16 v[102:105], v[156:159], v[210:213], v[102:105]
	v_mfma_f32_16x16x32_bf16 v[94:97], v[148:151], v[218:221], v[94:97]
	v_mfma_f32_16x16x32_bf16 v[86:89], v[156:159], v[218:221], v[86:89]
	v_mfma_f32_16x16x32_bf16 v[78:81], v[148:151], v[226:229], v[78:81]
	v_mfma_f32_16x16x32_bf16 v[70:73], v[156:159], v[226:229], v[70:73]
	v_mfma_f32_16x16x32_bf16 v[122:125], v[160:163], v[198:201], v[122:125]
	v_mfma_f32_16x16x32_bf16 v[114:117], v[176:179], v[198:201], v[114:117]
	v_mfma_f32_16x16x32_bf16 v[106:109], v[160:163], v[206:209], v[106:109]
	v_mfma_f32_16x16x32_bf16 v[98:101], v[176:179], v[206:209], v[98:101]
	v_mfma_f32_16x16x32_bf16 v[90:93], v[160:163], v[214:217], v[90:93]
	v_mfma_f32_16x16x32_bf16 v[82:85], v[176:179], v[214:217], v[82:85]
	v_mfma_f32_16x16x32_bf16 v[74:77], v[160:163], v[222:225], v[74:77]
	v_mfma_f32_16x16x32_bf16 v[66:69], v[176:179], v[222:225], v[66:69]
	v_mfma_f32_16x16x32_bf16 v[122:125], v[168:171], v[202:205], v[122:125]
	v_mfma_f32_16x16x32_bf16 v[114:117], v[180:183], v[202:205], v[114:117]
	v_mfma_f32_16x16x32_bf16 v[106:109], v[168:171], v[210:213], v[106:109]
	v_mfma_f32_16x16x32_bf16 v[98:101], v[180:183], v[210:213], v[98:101]
	v_mfma_f32_16x16x32_bf16 v[90:93], v[168:171], v[218:221], v[90:93]
	v_mfma_f32_16x16x32_bf16 v[82:85], v[180:183], v[218:221], v[82:85]
	v_mfma_f32_16x16x32_bf16 v[74:77], v[168:171], v[226:229], v[74:77]
	v_mfma_f32_16x16x32_bf16 v[66:69], v[180:183], v[226:229], v[66:69]
	v_mfma_f32_16x16x32_bf16 v[62:65], v[140:143], v[234:237], v[62:65]
	v_mfma_f32_16x16x32_bf16 v[54:57], v[152:155], v[234:237], v[54:57]
	v_mfma_f32_16x16x32_bf16 v[46:49], v[140:143], v[242:245], v[46:49]
	v_mfma_f32_16x16x32_bf16 v[38:41], v[152:155], v[242:245], v[38:41]
	v_mfma_f32_16x16x32_bf16 v[30:33], v[140:143], v[136:139], v[30:33]
	v_mfma_f32_16x16x32_bf16 v[22:25], v[152:155], v[136:139], v[22:25]
	v_mfma_f32_16x16x32_bf16 v[14:17], v[140:143], v[184:187], v[14:17]
	v_mfma_f32_16x16x32_bf16 v[6:9], v[152:155], v[184:187], v[6:9]
	v_mfma_f32_16x16x32_bf16 v[62:65], v[148:151], v[238:241], v[62:65]
	v_mfma_f32_16x16x32_bf16 v[54:57], v[156:159], v[238:241], v[54:57]
	v_mfma_f32_16x16x32_bf16 v[46:49], v[148:151], v[246:249], v[46:49]
	v_mfma_f32_16x16x32_bf16 v[38:41], v[156:159], v[246:249], v[38:41]
	v_mfma_f32_16x16x32_bf16 v[30:33], v[148:151], v[230:233], v[30:33]
	v_mfma_f32_16x16x32_bf16 v[22:25], v[156:159], v[230:233], v[22:25]
	v_mfma_f32_16x16x32_bf16 v[14:17], v[148:151], v[164:167], v[14:17]
	v_mfma_f32_16x16x32_bf16 v[6:9], v[156:159], v[164:167], v[6:9]
	v_mfma_f32_16x16x32_bf16 v[58:61], v[160:163], v[234:237], v[58:61]
	v_mfma_f32_16x16x32_bf16 v[50:53], v[176:179], v[234:237], v[50:53]
	v_mfma_f32_16x16x32_bf16 v[42:45], v[160:163], v[242:245], v[42:45]
	v_mfma_f32_16x16x32_bf16 v[34:37], v[176:179], v[242:245], v[34:37]
	v_mfma_f32_16x16x32_bf16 v[26:29], v[160:163], v[136:139], v[26:29]
	v_mfma_f32_16x16x32_bf16 v[18:21], v[176:179], v[136:139], v[18:21]
	v_mfma_f32_16x16x32_bf16 v[10:13], v[160:163], v[184:187], v[10:13]
	v_mfma_f32_16x16x32_bf16 v[2:5], v[176:179], v[184:187], v[2:5]
	v_mfma_f32_16x16x32_bf16 v[58:61], v[168:171], v[238:241], v[58:61]
	v_mfma_f32_16x16x32_bf16 v[50:53], v[180:183], v[238:241], v[50:53]
	v_mfma_f32_16x16x32_bf16 v[42:45], v[168:171], v[246:249], v[42:45]
	v_mfma_f32_16x16x32_bf16 v[34:37], v[180:183], v[246:249], v[34:37]
	v_mfma_f32_16x16x32_bf16 v[26:29], v[168:171], v[230:233], v[26:29]
	v_mfma_f32_16x16x32_bf16 v[18:21], v[180:183], v[230:233], v[18:21]
	v_mfma_f32_16x16x32_bf16 v[10:13], v[168:171], v[164:167], v[10:13]
	v_mfma_f32_16x16x32_bf16 v[2:5], v[180:183], v[164:167], v[2:5]
	s_waitcnt vmcnt(0)
	s_barrier
	s_setprio 0
	s_branch .Lgd_j2
.Lgd_y2:
	s_add_i32 m0, s55, 0x2000
	ds_read_b128 v[198:201], v147 offset:32768
	ds_read_b128 v[206:209], v147 offset:34816
	global_load_lds_dwordx4 v130, s[98:99] offset:-4096
	ds_read_b128 v[214:217], v147 offset:36864
	ds_read_b128 v[222:225], v147 offset:38912
	ds_read_b128 v[202:205], v147 offset:33792
	global_load_lds_dwordx4 v131, s[98:99]
	ds_read_b128 v[210:213], v147 offset:35840
	ds_read_b128 v[218:221], v147 offset:37888
	ds_read_b128 v[226:229], v147 offset:39936
	s_add_i32 m0, s55, 0x6000
	ds_read_b128 v[140:143], v174
	ds_read_b128 v[152:155], v174 offset:2048
	global_load_lds_dwordx4 v133, s[98:99] offset:-4096
	ds_read_b128 v[148:151], v174 offset:1024
	ds_read_b128 v[156:159], v174 offset:3072
	ds_read_b128 v[160:163], v250
	global_load_lds_dwordx4 v135, s[98:99]
	ds_read_b128 v[176:179], v250 offset:2048
	ds_read_b128 v[168:171], v250 offset:1024
	ds_read_b128 v[180:183], v250 offset:3072
	s_add_i32 m0, s55, 0x8000
	ds_read_b128 v[234:237], v147 offset:49152
	ds_read_b128 v[242:245], v147 offset:51200
	global_load_lds_dwordx4 v190, s[30:31] offset:-4096
	ds_read_b128 v[136:139], v147 offset:53248
	ds_read_b128 v[184:187], v147 offset:55296
	ds_read_b128 v[238:241], v147 offset:50176
	global_load_lds_dwordx4 v188, s[30:31]
	ds_read_b128 v[246:249], v147 offset:52224
	ds_read_b128 v[230:233], v147 offset:54272
	ds_read_b128 v[164:167], v147 offset:56320
	s_setprio 1
	s_waitcnt vmcnt(6) lgkmcnt(0)
	s_barrier
	v_mfma_f32_16x16x32_bf16 v[126:129], v[140:143], v[198:201], v[126:129]
	v_mfma_f32_16x16x32_bf16 v[118:121], v[152:155], v[198:201], v[118:121]
	s_add_i32 m0, s55, 0xc000
	v_mfma_f32_16x16x32_bf16 v[110:113], v[140:143], v[206:209], v[110:113]
	v_mfma_f32_16x16x32_bf16 v[102:105], v[152:155], v[206:209], v[102:105]
	global_load_lds_dwordx4 v194, s[30:31] offset:-4096
	v_mfma_f32_16x16x32_bf16 v[94:97], v[140:143], v[214:217], v[94:97]
	v_mfma_f32_16x16x32_bf16 v[86:89], v[152:155], v[214:217], v[86:89]
	v_mfma_f32_16x16x32_bf16 v[78:81], v[140:143], v[222:225], v[78:81]
	v_mfma_f32_16x16x32_bf16 v[70:73], v[152:155], v[222:225], v[70:73]
	v_mfma_f32_16x16x32_bf16 v[126:129], v[148:151], v[202:205], v[126:129]
	v_mfma_f32_16x16x32_bf16 v[118:121], v[156:159], v[202:205], v[118:121]
	v_mfma_f32_16x16x32_bf16 v[110:113], v[148:151], v[210:213], v[110:113]
	v_mfma_f32_16x16x32_bf16 v[102:105], v[156:159], v[210:213], v[102:105]
	global_load_lds_dwordx4 v192, s[30:31]
	v_mfma_f32_16x16x32_bf16 v[94:97], v[148:151], v[218:221], v[94:97]
	v_mfma_f32_16x16x32_bf16 v[86:89], v[156:159], v[218:221], v[86:89]
	v_mfma_f32_16x16x32_bf16 v[78:81], v[148:151], v[226:229], v[78:81]
	v_mfma_f32_16x16x32_bf16 v[70:73], v[156:159], v[226:229], v[70:73]
	v_mfma_f32_16x16x32_bf16 v[122:125], v[160:163], v[198:201], v[122:125]
	v_mfma_f32_16x16x32_bf16 v[114:117], v[176:179], v[198:201], v[114:117]
	v_mfma_f32_16x16x32_bf16 v[106:109], v[160:163], v[206:209], v[106:109]
	v_mfma_f32_16x16x32_bf16 v[98:101], v[176:179], v[206:209], v[98:101]
	v_mfma_f32_16x16x32_bf16 v[90:93], v[160:163], v[214:217], v[90:93]
	v_mfma_f32_16x16x32_bf16 v[82:85], v[176:179], v[214:217], v[82:85]
	v_mfma_f32_16x16x32_bf16 v[74:77], v[160:163], v[222:225], v[74:77]
	v_mfma_f32_16x16x32_bf16 v[66:69], v[176:179], v[222:225], v[66:69]
	v_mfma_f32_16x16x32_bf16 v[122:125], v[168:171], v[202:205], v[122:125]
	v_mfma_f32_16x16x32_bf16 v[114:117], v[180:183], v[202:205], v[114:117]
	v_mfma_f32_16x16x32_bf16 v[106:109], v[168:171], v[210:213], v[106:109]
	v_mfma_f32_16x16x32_bf16 v[98:101], v[180:183], v[210:213], v[98:101]
	v_mfma_f32_16x16x32_bf16 v[90:93], v[168:171], v[218:221], v[90:93]
	v_mfma_f32_16x16x32_bf16 v[82:85], v[180:183], v[218:221], v[82:85]
	v_mfma_f32_16x16x32_bf16 v[74:77], v[168:171], v[226:229], v[74:77]
	v_mfma_f32_16x16x32_bf16 v[66:69], v[180:183], v[226:229], v[66:69]
	v_mfma_f32_16x16x32_bf16 v[62:65], v[140:143], v[234:237], v[62:65]
	v_mfma_f32_16x16x32_bf16 v[54:57], v[152:155], v[234:237], v[54:57]
	v_mfma_f32_16x16x32_bf16 v[46:49], v[140:143], v[242:245], v[46:49]
	v_mfma_f32_16x16x32_bf16 v[38:41], v[152:155], v[242:245], v[38:41]
	v_mfma_f32_16x16x32_bf16 v[30:33], v[140:143], v[136:139], v[30:33]
	v_mfma_f32_16x16x32_bf16 v[22:25], v[152:155], v[136:139], v[22:25]
	v_mfma_f32_16x16x32_bf16 v[14:17], v[140:143], v[184:187], v[14:17]
	v_mfma_f32_16x16x32_bf16 v[6:9], v[152:155], v[184:187], v[6:9]
	v_mfma_f32_16x16x32_bf16 v[62:65], v[148:151], v[238:241], v[62:65]
	v_mfma_f32_16x16x32_bf16 v[54:57], v[156:159], v[238:241], v[54:57]
	v_mfma_f32_16x16x32_bf16 v[46:49], v[148:151], v[246:249], v[46:49]
	v_mfma_f32_16x16x32_bf16 v[38:41], v[156:159], v[246:249], v[38:41]
	v_mfma_f32_16x16x32_bf16 v[30:33], v[148:151], v[230:233], v[30:33]
	v_mfma_f32_16x16x32_bf16 v[22:25], v[156:159], v[230:233], v[22:25]
	v_mfma_f32_16x16x32_bf16 v[14:17], v[148:151], v[164:167], v[14:17]
	v_mfma_f32_16x16x32_bf16 v[6:9], v[156:159], v[164:167], v[6:9]
	v_mfma_f32_16x16x32_bf16 v[58:61], v[160:163], v[234:237], v[58:61]
	v_mfma_f32_16x16x32_bf16 v[50:53], v[176:179], v[234:237], v[50:53]
	v_mfma_f32_16x16x32_bf16 v[42:45], v[160:163], v[242:245], v[42:45]
	v_mfma_f32_16x16x32_bf16 v[34:37], v[176:179], v[242:245], v[34:37]
	v_mfma_f32_16x16x32_bf16 v[26:29], v[160:163], v[136:139], v[26:29]
	v_mfma_f32_16x16x32_bf16 v[18:21], v[176:179], v[136:139], v[18:21]
	v_mfma_f32_16x16x32_bf16 v[10:13], v[160:163], v[184:187], v[10:13]
	v_mfma_f32_16x16x32_bf16 v[2:5], v[176:179], v[184:187], v[2:5]
	v_mfma_f32_16x16x32_bf16 v[58:61], v[168:171], v[238:241], v[58:61]
	v_mfma_f32_16x16x32_bf16 v[50:53], v[180:183], v[238:241], v[50:53]
	v_mfma_f32_16x16x32_bf16 v[42:45], v[168:171], v[246:249], v[42:45]
	v_mfma_f32_16x16x32_bf16 v[34:37], v[180:183], v[246:249], v[34:37]
	v_mfma_f32_16x16x32_bf16 v[26:29], v[168:171], v[230:233], v[26:29]
	v_mfma_f32_16x16x32_bf16 v[18:21], v[180:183], v[230:233], v[18:21]
	v_mfma_f32_16x16x32_bf16 v[10:13], v[168:171], v[164:167], v[10:13]
	v_mfma_f32_16x16x32_bf16 v[2:5], v[180:183], v[164:167], v[2:5]
	s_waitcnt vmcnt(2)
	s_barrier
	s_setprio 0
.Lgd_j2:
	s_add_i32 s76, s76, 2
	s_add_u32 s20, s20, 0x100
	s_addc_u32 s21, s21, 0
	s_add_u32 s74, s74, 0x100
	s_addc_u32 s75, s75, 0
	s_cmp_gt_u32 s76, 29
	s_cbranch_scc0 .LBB0_1089
	v_mov_b32_e32 v187, 1
	v_mov_b64_e32 v[166:167], 0x1ff
	s_and_b64 vcc, exec, s[64:65]
	s_cbranch_vccz .LBB0_1092
	s_barrier
